# spatial-gating LayerNorm preamble: each lane owns interleaved 8-column chunks of its row so the 4 lanes of a row read 64 contiguous bytes per load instruction (16 lines per instruction instead of 64);
# speedup vs baseline: 1.0115x; 1.0038x over previous
; __device__ __forceinline__ float bflo(unsigned w) { return __uint_as_float(w << 16); }
; __device__ __forceinline__ float bfhi(unsigned w) { return __uint_as_float(w & 0xffff0000u); }
; __device__ __forceinline__ float shfl_x(float v, int m, int lane) { return __builtin_bit_cast(float, __builtin_amdgcn_ds_bpermute((lane ^ m) << 2, __builtin_bit_cast(int, v))); }
; __device__ __forceinline__ void sgu_unit(LAS unsigned char* lds, const bf16_t* proj, bf16_t* Y, const bf16_t* wsb  , const float* lnw, const float* lnb, const float* bs  , int row0, unsigned long long* gss, const int wave_s) {
;     ...
;         const int s = tid >> 2, q = tid & 3;
;         const u32x4* src = (const u32x4*)(proj + (size_t)(row0 + s) * PJP + PC_CV + 64 * q);
;         float v[64]; float sum = 0.f;
; #pragma unroll
;         for (int i = 0; i < 8; ++i) { const u32x4 w = src[i];
;             v[8 * i + 0] = bflo(w.x); v[8 * i + 1] = bfhi(w.x); v[8 * i + 2] = bflo(w.y); v[8 * i + 3] = bfhi(w.y);
;             v[8 * i + 4] = bflo(w.z); v[8 * i + 5] = bfhi(w.z); v[8 * i + 6] = bflo(w.w); v[8 * i + 7] = bfhi(w.w); }
; #pragma unroll
;         for (int i = 0; i < 64; ++i) sum += v[i];
;         sum += shfl_x(sum, 1, lane); sum += shfl_x(sum, 2, lane);
;         const float mu = sum * (1.0f / 256.0f); float sq = 0.f;
.LBB0_835:
	s_ashr_i32 s2, s4, 31
	s_lshr_b32 s2, s2, 23
	s_add_i32 s2, s4, s2
	s_and_b32 s2, s2, 0x1fffe00
	s_sub_i32 s2, s4, s2
	s_load_dwordx2 s[6:7], s[0:1], 0xb8
	s_waitcnt lgkmcnt(0)
	s_load_dwordx2 s[8:9], s[0:1], 0xb8
	s_waitcnt lgkmcnt(0)
	s_load_dwordx2 s[10:11], s[0:1], 0xb8
	s_waitcnt lgkmcnt(0)
	s_load_dwordx2 s[12:13], s[0:1], 0xb8
	s_waitcnt lgkmcnt(0)
	v_mbcnt_lo_u32_b32 v10, -1, 0
	v_mbcnt_hi_u32_b32 v10, -1, v10
	s_lshl_b32 s2, s2, 7
	v_or_b32_e32 v21, s63, v10
	v_ashrrev_i32_e32 v6, 2, v21
	v_add_u32_e32 v0, s2, v6
	v_mov_b64_e32 v[2:3], s[6:7]
	v_mad_i64_i32 v[4:5], s[6:7], v0, s85, v[2:3]
	v_lshlrev_b32_e32 v0, 6, v10
	v_and_b32_e32 v75, 0xc0, v0
	v_lshrrev_b32_e32 v0, 2, v75
	v_lshl_add_u64 v[4:5], v[4:5], 0, v[0:1]
	s_mov_b64 s[6:7], 0x10000000
	v_lshl_add_u64 v[4:5], v[4:5], 0, s[6:7]
	global_load_dwordx4 v[12:15], v[4:5], off offset:3584
	global_load_dwordx4 v[78:81], v[4:5], off offset:3968
	v_and_b32_e32 v9, 63, v10
	v_readfirstlane_b32 s3, v21
	v_lshlrev_b32_e32 v21, 2, v9
	v_and_b32_e32 v8, 31, v10
	v_bfe_u32 v10, v10, 5, 1
	s_ashr_i32 s22, s2, 31
	v_readlane_b32 s24, v255, 8
	v_readlane_b32 s25, v255, 9
	s_waitcnt vmcnt(0) lgkmcnt(0)
	v_lshlrev_b32_e32 v7, 16, v12
	v_and_b32_e32 v77, 0xffff0000, v12
	v_lshlrev_b32_e32 v76, 16, v13
	v_and_b32_e32 v74, 0xffff0000, v13
	v_lshlrev_b32_e32 v73, 16, v14
	v_and_b32_e32 v72, 0xffff0000, v14
	v_lshlrev_b32_e32 v71, 16, v15
	v_and_b32_e32 v69, 0xffff0000, v15
	global_load_dwordx4 v[12:15], v[4:5], off offset:3648
	v_lshlrev_b32_e32 v23, 16, v78
	v_and_b32_e32 v18, 0xffff0000, v78
	v_lshlrev_b32_e32 v11, 16, v81
	v_and_b32_e32 v0, 0xffff0000, v81
	s_waitcnt vmcnt(0) lgkmcnt(0)
	v_lshlrev_b32_e32 v70, 16, v12
	v_and_b32_e32 v68, 0xffff0000, v12
	v_lshlrev_b32_e32 v67, 16, v13
	v_and_b32_e32 v65, 0xffff0000, v13
	v_lshlrev_b32_e32 v64, 16, v14
	v_and_b32_e32 v63, 0xffff0000, v14
	v_lshlrev_b32_e32 v62, 16, v15
	v_and_b32_e32 v60, 0xffff0000, v15
	global_load_dwordx4 v[12:15], v[4:5], off offset:3712
	s_waitcnt vmcnt(0) lgkmcnt(0)
	v_lshlrev_b32_e32 v61, 16, v12
	v_and_b32_e32 v59, 0xffff0000, v12
	v_lshlrev_b32_e32 v58, 16, v13
	v_and_b32_e32 v57, 0xffff0000, v13
	v_lshlrev_b32_e32 v56, 16, v14
	v_and_b32_e32 v55, 0xffff0000, v14
	v_lshlrev_b32_e32 v54, 16, v15
	v_and_b32_e32 v52, 0xffff0000, v15
	global_load_dwordx4 v[12:15], v[4:5], off offset:3776
	s_waitcnt vmcnt(0) lgkmcnt(0)
	v_lshlrev_b32_e32 v53, 16, v12
	v_and_b32_e32 v51, 0xffff0000, v12
	v_lshlrev_b32_e32 v50, 16, v13
	v_and_b32_e32 v49, 0xffff0000, v13
	v_lshlrev_b32_e32 v47, 16, v14
	v_and_b32_e32 v46, 0xffff0000, v14
	v_lshlrev_b32_e32 v45, 16, v15
	v_and_b32_e32 v43, 0xffff0000, v15
	global_load_dwordx4 v[12:15], v[4:5], off offset:3840
	s_waitcnt vmcnt(0) lgkmcnt(0)
	v_lshlrev_b32_e32 v44, 16, v12
	v_and_b32_e32 v42, 0xffff0000, v12
	v_lshlrev_b32_e32 v41, 16, v13
	v_and_b32_e32 v40, 0xffff0000, v13
	v_lshlrev_b32_e32 v39, 16, v14
	v_and_b32_e32 v38, 0xffff0000, v14
	v_lshlrev_b32_e32 v37, 16, v15
	v_and_b32_e32 v35, 0xffff0000, v15
	global_load_dwordx4 v[12:15], v[4:5], off offset:3904
	s_waitcnt vmcnt(0) lgkmcnt(0)
	v_lshlrev_b32_e32 v36, 16, v12
	v_and_b32_e32 v34, 0xffff0000, v12
	v_lshlrev_b32_e32 v32, 16, v13
	v_and_b32_e32 v30, 0xffff0000, v13
	v_lshlrev_b32_e32 v28, 16, v14
	v_and_b32_e32 v26, 0xffff0000, v14
	v_lshlrev_b32_e32 v24, 16, v15
	v_and_b32_e32 v20, 0xffff0000, v15
	v_lshlrev_b32_e32 v15, 16, v79
	v_and_b32_e32 v14, 0xffff0000, v79
	v_lshlrev_b32_e32 v13, 16, v80
	v_and_b32_e32 v12, 0xffff0000, v80
	global_load_dwordx4 v[78:81], v[4:5], off offset:4032
	v_add_f32_e32 v4, 0, v7
	v_add_f32_e32 v4, v4, v77
	v_add_f32_e32 v4, v4, v76
	v_add_f32_e32 v4, v4, v74
	v_add_f32_e32 v4, v4, v73
	v_add_f32_e32 v4, v4, v72
	v_add_f32_e32 v4, v4, v71
	v_add_f32_e32 v4, v4, v69
	v_add_f32_e32 v4, v4, v70
	v_add_f32_e32 v4, v4, v68
	v_add_f32_e32 v4, v4, v67
	v_add_f32_e32 v4, v4, v65
	v_add_f32_e32 v4, v4, v64
	v_add_f32_e32 v4, v4, v63
	v_add_f32_e32 v4, v4, v62
	v_add_f32_e32 v4, v4, v60
	v_add_f32_e32 v4, v4, v61
	v_add_f32_e32 v4, v4, v59
	v_add_f32_e32 v4, v4, v58
	v_add_f32_e32 v4, v4, v57
	v_add_f32_e32 v4, v4, v56
	v_add_f32_e32 v4, v4, v55
	v_add_f32_e32 v4, v4, v54
	v_add_f32_e32 v4, v4, v52
	v_add_f32_e32 v4, v4, v53
	v_add_f32_e32 v4, v4, v51
	v_add_f32_e32 v4, v4, v50
	v_add_f32_e32 v4, v4, v49
	v_add_f32_e32 v4, v4, v47
	v_add_f32_e32 v4, v4, v46
	v_add_f32_e32 v4, v4, v45
	v_add_f32_e32 v4, v4, v43
	v_add_f32_e32 v4, v4, v44
	v_add_f32_e32 v4, v4, v42
	v_add_f32_e32 v4, v4, v41
	v_add_f32_e32 v4, v4, v40
	v_add_f32_e32 v4, v4, v39
	v_add_f32_e32 v4, v4, v38
	v_add_f32_e32 v4, v4, v37
	v_add_f32_e32 v4, v4, v35
	v_add_f32_e32 v4, v4, v36
	v_add_f32_e32 v4, v4, v34
	v_add_f32_e32 v4, v4, v32
	v_add_f32_e32 v4, v4, v30
	v_add_f32_e32 v4, v4, v28
	v_add_f32_e32 v4, v4, v26
	v_add_f32_e32 v4, v4, v24
	v_add_f32_e32 v4, v4, v20
	v_add_f32_e32 v4, v4, v23
	v_add_f32_e32 v4, v4, v18
	v_add_f32_e32 v4, v4, v15
	v_add_f32_e32 v4, v4, v14
	v_add_f32_e32 v4, v4, v13
	v_add_f32_e32 v4, v4, v12
	v_add_f32_e32 v4, v4, v11
	v_add_f32_e32 v4, v4, v0
	v_xor_b32_e32 v5, 4, v21
	s_waitcnt vmcnt(0) lgkmcnt(0)
	v_lshlrev_b32_e32 v33, 16, v78
	v_and_b32_e32 v31, 0xffff0000, v78
	v_add_f32_e32 v4, v4, v33
	v_lshlrev_b32_e32 v29, 16, v79
	v_add_f32_e32 v4, v4, v31
	v_and_b32_e32 v27, 0xffff0000, v79
	v_add_f32_e32 v4, v4, v29
	v_lshlrev_b32_e32 v25, 16, v80
	v_add_f32_e32 v4, v4, v27
	v_and_b32_e32 v22, 0xffff0000, v80
	v_add_f32_e32 v4, v4, v25
	v_lshlrev_b32_e32 v19, 16, v81
	v_add_f32_e32 v4, v4, v22
	v_and_b32_e32 v17, 0xffff0000, v81
	v_add_f32_e32 v4, v4, v19
	v_add_f32_e32 v4, v4, v17
	ds_bpermute_b32 v48, v5, v4
	s_waitcnt lgkmcnt(0)
; __device__ __forceinline__ unsigned cvtpk(float lo, float hi) { unsigned r; asm volatile("v_cvt_pk_bf16_f32 %0, %1, %2" : "=v"(r) : "v"(lo), "v"(hi)); return r; }
; __device__ __forceinline__ float shfl_x(float v, int m, int lane) { return __builtin_bit_cast(float, __builtin_amdgcn_ds_bpermute((lane ^ m) << 2, __builtin_bit_cast(int, v))); }
; __device__ __forceinline__ void sgu_unit(LAS unsigned char* lds, const bf16_t* proj, bf16_t* Y, const bf16_t* wsb  , const float* lnw, const float* lnb, const float* bs  , int row0, unsigned long long* gss, const int wave_s) {
;     ...
;         sum += shfl_x(sum, 1, lane); sum += shfl_x(sum, 2, lane);
;         const float mu = sum * (1.0f / 256.0f); float sq = 0.f;
; #pragma unroll
;         for (int i = 0; i < 64; ++i) { v[i] -= mu; sq += v[i] * v[i]; }
;         sq += shfl_x(sq, 1, lane); sq += shfl_x(sq, 2, lane);
;         const float rstd = 1.0f / sqrtf(sq * (1.0f / 256.0f) + EPS);
; #pragma unroll
;         for (int i = 0; i < 64; i += 2) {
;             const int c = 64 * q + i;
;             const float a = v[i] * rstd * lnw[c] + lnb[c], b = v[i + 1] * rstd * lnw[c + 1] + lnb[c + 1];
;             const unsigned w = cvtpk(a, b);
;             vt[c * SSTR + s] = (unsigned short)(w & 0xffffu); vt[(c + 1) * SSTR + s] = (unsigned short)(w >> 16);
	v_add_f32_e32 v4, v4, v48
	v_xor_b32_e32 v48, 8, v21
	ds_bpermute_b32 v66, v48, v4
	s_waitcnt lgkmcnt(0)
	v_add_f32_e32 v4, v4, v66
	v_fmac_f32_e32 v77, 0xbb800000, v4
	v_fmac_f32_e32 v7, 0xbb800000, v4
	v_mul_f32_e32 v66, v77, v77
	v_fmac_f32_e32 v66, v7, v7
	v_fmac_f32_e32 v76, 0xbb800000, v4
	v_fmac_f32_e32 v66, v76, v76
	v_fmac_f32_e32 v74, 0xbb800000, v4
	v_fmac_f32_e32 v66, v74, v74
	v_fmac_f32_e32 v73, 0xbb800000, v4
	v_fmac_f32_e32 v66, v73, v73
	v_fmac_f32_e32 v72, 0xbb800000, v4
	v_fmac_f32_e32 v66, v72, v72
	v_fmac_f32_e32 v71, 0xbb800000, v4
	v_fmac_f32_e32 v66, v71, v71
	v_fmac_f32_e32 v69, 0xbb800000, v4
	v_fmac_f32_e32 v66, v69, v69
	v_fmac_f32_e32 v70, 0xbb800000, v4
	v_fmac_f32_e32 v66, v70, v70
	v_fmac_f32_e32 v68, 0xbb800000, v4
	v_fmac_f32_e32 v66, v68, v68
	v_fmac_f32_e32 v67, 0xbb800000, v4
	v_fmac_f32_e32 v66, v67, v67
	v_fmac_f32_e32 v65, 0xbb800000, v4
	v_fmac_f32_e32 v66, v65, v65
	v_fmac_f32_e32 v64, 0xbb800000, v4
	v_fmac_f32_e32 v66, v64, v64
	v_fmac_f32_e32 v63, 0xbb800000, v4
	v_fmac_f32_e32 v66, v63, v63
	v_fmac_f32_e32 v62, 0xbb800000, v4
	v_fmac_f32_e32 v66, v62, v62
	v_fmac_f32_e32 v60, 0xbb800000, v4
	v_fmac_f32_e32 v66, v60, v60
	v_fmac_f32_e32 v61, 0xbb800000, v4
	v_fmac_f32_e32 v66, v61, v61
	v_fmac_f32_e32 v59, 0xbb800000, v4
	v_fmac_f32_e32 v66, v59, v59
	v_fmac_f32_e32 v58, 0xbb800000, v4
	v_fmac_f32_e32 v66, v58, v58
	v_fmac_f32_e32 v57, 0xbb800000, v4
	v_fmac_f32_e32 v66, v57, v57
	v_fmac_f32_e32 v56, 0xbb800000, v4
	v_fmac_f32_e32 v66, v56, v56
	v_fmac_f32_e32 v55, 0xbb800000, v4
	v_fmac_f32_e32 v66, v55, v55
	v_fmac_f32_e32 v54, 0xbb800000, v4
	v_fmac_f32_e32 v66, v54, v54
	v_fmac_f32_e32 v52, 0xbb800000, v4
	v_fmac_f32_e32 v66, v52, v52
	v_fmac_f32_e32 v53, 0xbb800000, v4
	v_fmac_f32_e32 v66, v53, v53
	v_fmac_f32_e32 v51, 0xbb800000, v4
	v_fmac_f32_e32 v66, v51, v51
	v_fmac_f32_e32 v50, 0xbb800000, v4
	v_fmac_f32_e32 v66, v50, v50
	v_fmac_f32_e32 v49, 0xbb800000, v4
	v_fmac_f32_e32 v66, v49, v49
	v_fmac_f32_e32 v47, 0xbb800000, v4
	v_fmac_f32_e32 v66, v47, v47
	v_fmac_f32_e32 v46, 0xbb800000, v4
	v_fmac_f32_e32 v66, v46, v46
	v_fmac_f32_e32 v45, 0xbb800000, v4
	v_fmac_f32_e32 v66, v45, v45
	v_fmac_f32_e32 v43, 0xbb800000, v4
	v_fmac_f32_e32 v66, v43, v43
	v_fmac_f32_e32 v44, 0xbb800000, v4
	v_fmac_f32_e32 v66, v44, v44
	v_fmac_f32_e32 v42, 0xbb800000, v4
	v_fmac_f32_e32 v66, v42, v42
	v_fmac_f32_e32 v41, 0xbb800000, v4
	v_fmac_f32_e32 v66, v41, v41
	v_fmac_f32_e32 v40, 0xbb800000, v4
	v_fmac_f32_e32 v66, v40, v40
	v_fmac_f32_e32 v39, 0xbb800000, v4
	v_fmac_f32_e32 v66, v39, v39
	v_fmac_f32_e32 v38, 0xbb800000, v4
	v_fmac_f32_e32 v66, v38, v38
	v_fmac_f32_e32 v37, 0xbb800000, v4
	v_fmac_f32_e32 v66, v37, v37
	v_fmac_f32_e32 v35, 0xbb800000, v4
	v_fmac_f32_e32 v66, v35, v35
	v_fmac_f32_e32 v36, 0xbb800000, v4
	v_fmac_f32_e32 v66, v36, v36
	v_fmac_f32_e32 v34, 0xbb800000, v4
	v_fmac_f32_e32 v66, v34, v34
	v_fmac_f32_e32 v32, 0xbb800000, v4
	v_fmac_f32_e32 v66, v32, v32
	v_fmac_f32_e32 v30, 0xbb800000, v4
	v_fmac_f32_e32 v66, v30, v30
	v_fmac_f32_e32 v28, 0xbb800000, v4
	v_fmac_f32_e32 v66, v28, v28
	v_fmac_f32_e32 v26, 0xbb800000, v4
	v_fmac_f32_e32 v66, v26, v26
	v_fmac_f32_e32 v24, 0xbb800000, v4
	v_fmac_f32_e32 v66, v24, v24
	v_fmac_f32_e32 v20, 0xbb800000, v4
	v_fmac_f32_e32 v66, v20, v20
	v_fmac_f32_e32 v23, 0xbb800000, v4
	v_fmac_f32_e32 v66, v23, v23
	v_fmac_f32_e32 v18, 0xbb800000, v4
	v_fmac_f32_e32 v66, v18, v18
	v_fmac_f32_e32 v15, 0xbb800000, v4
	v_fmac_f32_e32 v66, v15, v15
	v_fmac_f32_e32 v14, 0xbb800000, v4
	v_fmac_f32_e32 v66, v14, v14
	v_fmac_f32_e32 v13, 0xbb800000, v4
	v_fmac_f32_e32 v66, v13, v13
	v_fmac_f32_e32 v12, 0xbb800000, v4
	v_fmac_f32_e32 v66, v12, v12
	v_fmac_f32_e32 v11, 0xbb800000, v4
	v_fmac_f32_e32 v66, v11, v11
	v_fmac_f32_e32 v0, 0xbb800000, v4
	v_fmac_f32_e32 v66, v0, v0
	v_fmac_f32_e32 v33, 0xbb800000, v4
	v_fmac_f32_e32 v66, v33, v33
	v_fmac_f32_e32 v31, 0xbb800000, v4
	v_fmac_f32_e32 v66, v31, v31
	v_fmac_f32_e32 v29, 0xbb800000, v4
	v_fmac_f32_e32 v66, v29, v29
	v_fmac_f32_e32 v27, 0xbb800000, v4
	v_fmac_f32_e32 v66, v27, v27
	v_fmac_f32_e32 v25, 0xbb800000, v4
	v_fmac_f32_e32 v66, v25, v25
	v_fmac_f32_e32 v22, 0xbb800000, v4
	v_fmac_f32_e32 v66, v22, v22
	v_fmac_f32_e32 v19, 0xbb800000, v4
	v_fmac_f32_e32 v66, v19, v19
	v_fmac_f32_e32 v17, 0xbb800000, v4
	v_fmac_f32_e32 v66, v17, v17
	ds_bpermute_b32 v4, v5, v66
	s_waitcnt lgkmcnt(0)
	v_add_f32_e32 v4, v66, v4
	ds_bpermute_b32 v5, v48, v4
	s_waitcnt lgkmcnt(0)
	v_add_f32_e32 v4, v4, v5
	v_fmamk_f32 v4, v4, 0x3b800000, v226
	s_ashr_i32 s6, s3, 7
	s_lshr_b32 s7, s3, 1
	s_lshl_b32 s5, s6, 6
	v_rsq_f32_e32 v48, v4
	s_nop 0
	v_lshrrev_b32_e32 v66, 1, v75
	v_lshlrev_b32_e32 v78, 1, v6
	v_mul_f32_e32 v79, v7, v48
	global_load_dwordx2 v[4:5], v66, s[14:15]
	global_load_dwordx2 v[6:7], v66, s[16:17]
	v_mul_f32_e32 v0, v0, v48
	s_and_b32 s7, s7, 32
	s_or_b32 s5, s5, s7
	s_movk_i32 s7, 0x88
	s_and_b32 s3, s3, 0xffffff80
	s_waitcnt vmcnt(0)
	v_fma_f32 v4, v4, v79, v6
	v_mul_f32_e32 v6, v77, v48
	v_fmac_f32_e32 v7, v5, v6
	v_cvt_pk_bf16_f32 v5, v4, v7
	v_mul_u32_u24_e32 v4, 0x22, v75
	v_add3_u32 v4, 0, v78, v4
	ds_write_b16 v4, v5
	ds_write_b16_d16_hi v4, v5 offset:272
	v_mul_f32_e32 v5, v76, v48
	global_load_dwordx2 v[6:7], v66, s[14:15] offset:8
	global_load_dwordx2 v[76:77], v66, s[16:17] offset:8
	s_waitcnt vmcnt(0)
	v_fma_f32 v5, v6, v5, v76
	v_mul_f32_e32 v6, v74, v48
	v_fmac_f32_e32 v77, v7, v6
	v_cvt_pk_bf16_f32 v5, v5, v77
	ds_write_b16 v4, v5 offset:544
	ds_write_b16_d16_hi v4, v5 offset:816
	global_load_dwordx2 v[6:7], v66, s[14:15] offset:16
	global_load_dwordx2 v[74:75], v66, s[16:17] offset:16
	v_mul_f32_e32 v5, v73, v48
	s_waitcnt vmcnt(0)
; __device__ __forceinline__ unsigned cvtpk(float lo, float hi) { unsigned r; asm volatile("v_cvt_pk_bf16_f32 %0, %1, %2" : "=v"(r) : "v"(lo), "v"(hi)); return r; }
; __device__ __forceinline__ void sgu_unit(LAS unsigned char* lds, const bf16_t* proj, bf16_t* Y, const bf16_t* wsb  , const float* lnw, const float* lnb, const float* bs  , int row0, unsigned long long* gss, const int wave_s) {
;     ...
;         for (int i = 0; i < 64; i += 2) {
;             const int c = 64 * q + i;
;             const float a = v[i] * rstd * lnw[c] + lnb[c], b = v[i + 1] * rstd * lnw[c + 1] + lnb[c + 1];
;             const unsigned w = cvtpk(a, b);
;             vt[c * SSTR + s] = (unsigned short)(w & 0xffffu); vt[(c + 1) * SSTR + s] = (unsigned short)(w >> 16);
;         }
	v_fma_f32 v5, v6, v5, v74
	v_mul_f32_e32 v6, v72, v48
	v_fmac_f32_e32 v75, v7, v6
	v_cvt_pk_bf16_f32 v5, v5, v75
	ds_write_b16 v4, v5 offset:1088
	ds_write_b16_d16_hi v4, v5 offset:1360
	global_load_dwordx2 v[6:7], v66, s[14:15] offset:24
	global_load_dwordx2 v[72:73], v66, s[16:17] offset:24
	v_mul_f32_e32 v5, v71, v48
	s_waitcnt vmcnt(0)
	v_fma_f32 v5, v6, v5, v72
	v_mul_f32_e32 v6, v69, v48
	v_fmac_f32_e32 v73, v7, v6
	v_cvt_pk_bf16_f32 v5, v5, v73
	ds_write_b16 v4, v5 offset:1632
	ds_write_b16_d16_hi v4, v5 offset:1904
	v_mul_f32_e32 v5, v70, v48
	global_load_dwordx2 v[6:7], v66, s[14:15] offset:128
	global_load_dwordx2 v[70:71], v66, s[16:17] offset:128
	s_waitcnt vmcnt(0)
	v_fma_f32 v5, v6, v5, v70
	v_mul_f32_e32 v6, v68, v48
	v_fmac_f32_e32 v71, v7, v6
	v_cvt_pk_bf16_f32 v5, v5, v71
	ds_write_b16 v4, v5 offset:8704
	ds_write_b16_d16_hi v4, v5 offset:8976
	global_load_dwordx2 v[6:7], v66, s[14:15] offset:136
	global_load_dwordx2 v[68:69], v66, s[16:17] offset:136
	v_mul_f32_e32 v5, v67, v48
	s_waitcnt vmcnt(0)
	v_fma_f32 v5, v6, v5, v68
	v_mul_f32_e32 v6, v65, v48
	v_fmac_f32_e32 v69, v7, v6
	v_cvt_pk_bf16_f32 v5, v5, v69
	ds_write_b16 v4, v5 offset:9248
	ds_write_b16_d16_hi v4, v5 offset:9520
	v_mul_f32_e32 v5, v64, v48
	global_load_dwordx2 v[6:7], v66, s[14:15] offset:144
	global_load_dwordx2 v[64:65], v66, s[16:17] offset:144
	s_waitcnt vmcnt(0)
	v_fma_f32 v5, v6, v5, v64
	v_mul_f32_e32 v6, v63, v48
	v_fmac_f32_e32 v65, v7, v6
	v_cvt_pk_bf16_f32 v5, v5, v65
	ds_write_b16 v4, v5 offset:9792
	ds_write_b16_d16_hi v4, v5 offset:10064
	v_mul_f32_e32 v5, v62, v48
	global_load_dwordx2 v[6:7], v66, s[14:15] offset:152
	global_load_dwordx2 v[62:63], v66, s[16:17] offset:152
	s_waitcnt vmcnt(0)
	v_fma_f32 v5, v6, v5, v62
	v_mul_f32_e32 v6, v60, v48
	v_fmac_f32_e32 v63, v7, v6
	v_cvt_pk_bf16_f32 v5, v5, v63
	ds_write_b16 v4, v5 offset:10336
	ds_write_b16_d16_hi v4, v5 offset:10608
	v_mul_f32_e32 v5, v61, v48
	global_load_dwordx2 v[6:7], v66, s[14:15] offset:256
	global_load_dwordx2 v[60:61], v66, s[16:17] offset:256
	s_waitcnt vmcnt(0)
	v_fma_f32 v5, v6, v5, v60
	v_mul_f32_e32 v6, v59, v48
	v_fmac_f32_e32 v61, v7, v6
	v_cvt_pk_bf16_f32 v5, v5, v61
	ds_write_b16 v4, v5 offset:17408
	ds_write_b16_d16_hi v4, v5 offset:17680
	v_mul_f32_e32 v5, v58, v48
	global_load_dwordx2 v[6:7], v66, s[14:15] offset:264
	global_load_dwordx2 v[58:59], v66, s[16:17] offset:264
	s_waitcnt vmcnt(0)
	v_fma_f32 v5, v6, v5, v58
	v_mul_f32_e32 v6, v57, v48
	v_fmac_f32_e32 v59, v7, v6
	v_cvt_pk_bf16_f32 v5, v5, v59
	ds_write_b16 v4, v5 offset:17952
	ds_write_b16_d16_hi v4, v5 offset:18224
	v_mul_f32_e32 v5, v56, v48
	global_load_dwordx2 v[6:7], v66, s[14:15] offset:272
	global_load_dwordx2 v[56:57], v66, s[16:17] offset:272
	s_waitcnt vmcnt(0)
	v_fma_f32 v5, v6, v5, v56
	v_mul_f32_e32 v6, v55, v48
	v_fmac_f32_e32 v57, v7, v6
	v_cvt_pk_bf16_f32 v5, v5, v57
	ds_write_b16 v4, v5 offset:18496
	ds_write_b16_d16_hi v4, v5 offset:18768
	v_mul_f32_e32 v5, v54, v48
	global_load_dwordx2 v[6:7], v66, s[14:15] offset:280
	global_load_dwordx2 v[54:55], v66, s[16:17] offset:280
	s_waitcnt vmcnt(0)
	v_fma_f32 v5, v6, v5, v54
	v_mul_f32_e32 v6, v52, v48
	v_fmac_f32_e32 v55, v7, v6
	v_cvt_pk_bf16_f32 v5, v5, v55
	ds_write_b16 v4, v5 offset:19040
	ds_write_b16_d16_hi v4, v5 offset:19312
	v_mul_f32_e32 v5, v53, v48
	global_load_dwordx2 v[6:7], v66, s[14:15] offset:384
	global_load_dwordx2 v[52:53], v66, s[16:17] offset:384
	s_waitcnt vmcnt(0)
	v_fma_f32 v5, v6, v5, v52
	v_mul_f32_e32 v6, v51, v48
	v_fmac_f32_e32 v53, v7, v6
	v_cvt_pk_bf16_f32 v5, v5, v53
	ds_write_b16 v4, v5 offset:26112
	ds_write_b16_d16_hi v4, v5 offset:26384
	v_mul_f32_e32 v5, v50, v48
	global_load_dwordx2 v[6:7], v66, s[14:15] offset:392
	global_load_dwordx2 v[50:51], v66, s[16:17] offset:392
	s_waitcnt vmcnt(0)
	v_fma_f32 v5, v6, v5, v50
	v_mul_f32_e32 v6, v49, v48
	v_fmac_f32_e32 v51, v7, v6
	v_cvt_pk_bf16_f32 v5, v5, v51
	ds_write_b16 v4, v5 offset:26656
	ds_write_b16_d16_hi v4, v5 offset:26928
	global_load_dwordx2 v[6:7], v66, s[14:15] offset:400
	global_load_dwordx2 v[50:51], v66, s[16:17] offset:400
	v_mul_f32_e32 v5, v47, v48
	s_waitcnt vmcnt(0)
	v_fma_f32 v5, v6, v5, v50
	v_mul_f32_e32 v6, v46, v48
	v_fmac_f32_e32 v51, v7, v6
	v_cvt_pk_bf16_f32 v5, v5, v51
	ds_write_b16 v4, v5 offset:27200
	ds_write_b16_d16_hi v4, v5 offset:27472
	global_load_dwordx2 v[6:7], v66, s[14:15] offset:408
	global_load_dwordx2 v[46:47], v66, s[16:17] offset:408
	v_mul_f32_e32 v5, v45, v48
	s_waitcnt vmcnt(0)
	v_fma_f32 v5, v6, v5, v46
	v_mul_f32_e32 v6, v43, v48
	v_fmac_f32_e32 v47, v7, v6
	v_cvt_pk_bf16_f32 v5, v5, v47
	ds_write_b16 v4, v5 offset:27744
	ds_write_b16_d16_hi v4, v5 offset:28016
	v_mul_f32_e32 v5, v44, v48
	global_load_dwordx2 v[6:7], v66, s[14:15] offset:512
	global_load_dwordx2 v[44:45], v66, s[16:17] offset:512
	s_waitcnt vmcnt(0)
	v_fma_f32 v5, v6, v5, v44
	v_mul_f32_e32 v6, v42, v48
	v_fmac_f32_e32 v45, v7, v6
	v_cvt_pk_bf16_f32 v5, v5, v45
	ds_write_b16 v4, v5 offset:34816
	ds_write_b16_d16_hi v4, v5 offset:35088
	global_load_dwordx2 v[6:7], v66, s[14:15] offset:520
	global_load_dwordx2 v[42:43], v66, s[16:17] offset:520
	v_mul_f32_e32 v5, v41, v48
	s_waitcnt vmcnt(0)
	v_fma_f32 v5, v6, v5, v42
	v_mul_f32_e32 v6, v40, v48
	v_fmac_f32_e32 v43, v7, v6
	v_cvt_pk_bf16_f32 v5, v5, v43
	ds_write_b16 v4, v5 offset:35360
	ds_write_b16_d16_hi v4, v5 offset:35632
	global_load_dwordx2 v[6:7], v66, s[14:15] offset:528
	global_load_dwordx2 v[40:41], v66, s[16:17] offset:528
	v_mul_f32_e32 v5, v39, v48
	s_waitcnt vmcnt(0)
; #define LAS __attribute__((address_space(3)))
; __device__ __forceinline__ unsigned cvtpk(float lo, float hi) { unsigned r; asm volatile("v_cvt_pk_bf16_f32 %0, %1, %2" : "=v"(r) : "v"(lo), "v"(hi)); return r; }
; __device__ __forceinline__ void sgu_unit(LAS unsigned char* lds, const bf16_t* proj, bf16_t* Y, const bf16_t* wsb  , const float* lnw, const float* lnb, const float* bs  , int row0, unsigned long long* gss, const int wave_s) {
;     ...
;         for (int i = 0; i < 64; i += 2) {
;             const int c = 64 * q + i;
;             const float a = v[i] * rstd * lnw[c] + lnb[c], b = v[i + 1] * rstd * lnw[c + 1] + lnb[c + 1];
;             const unsigned w = cvtpk(a, b);
;             vt[c * SSTR + s] = (unsigned short)(w & 0xffffu); vt[(c + 1) * SSTR + s] = (unsigned short)(w >> 16);
;         }
;     }
;     __syncthreads();
;     const int g = wid >> 1, dh = wid & 1;
;     const LAS unsigned char* ab = lds + ((64 * g + 32 * dh + r32) * SSTR + 8 * hi) * 2;
;     const bf16_t* wg = wsb + (size_t)g * 128 * 128;
; #pragma unroll 1
;     for (int tt = 0; tt < 4; ++tt) {
;         f32x16 acc;
; #pragma unroll
;         for (int r = 0; r < 16; ++r) acc[r] = 0.f;
;         const bf16_t* wrow = wg + (size_t)(32 * tt + r32) * 128 + 8 * hi;
	v_fma_f32 v5, v6, v5, v40
	v_mul_f32_e32 v6, v38, v48
	v_fmac_f32_e32 v41, v7, v6
	v_cvt_pk_bf16_f32 v5, v5, v41
	ds_write_b16 v4, v5 offset:35904
	ds_write_b16_d16_hi v4, v5 offset:36176
	global_load_dwordx2 v[6:7], v66, s[14:15] offset:536
	global_load_dwordx2 v[38:39], v66, s[16:17] offset:536
	v_mul_f32_e32 v5, v37, v48
	s_waitcnt vmcnt(0)
	v_fma_f32 v5, v5, v6, v38
	v_mul_f32_e32 v6, v35, v48
	v_fmac_f32_e32 v39, v6, v7
	v_cvt_pk_bf16_f32 v5, v5, v39
	ds_write_b16 v4, v5 offset:36448
	ds_write_b16_d16_hi v4, v5 offset:36720
	v_mul_f32_e32 v5, v36, v48
	global_load_dwordx2 v[6:7], v66, s[14:15] offset:640
	global_load_dwordx2 v[36:37], v66, s[16:17] offset:640
	s_waitcnt vmcnt(0)
	v_fma_f32 v5, v5, v6, v36
	v_mul_f32_e32 v6, v34, v48
	v_fmac_f32_e32 v37, v6, v7
	v_cvt_pk_bf16_f32 v5, v5, v37
	ds_write_b16 v4, v5 offset:43520
	ds_write_b16_d16_hi v4, v5 offset:43792
	global_load_dwordx2 v[6:7], v66, s[14:15] offset:648
	global_load_dwordx2 v[34:35], v66, s[16:17] offset:648
	v_mul_f32_e32 v5, v32, v48
	s_waitcnt vmcnt(0)
	v_fma_f32 v5, v5, v6, v34
	v_mul_f32_e32 v6, v30, v48
	v_fmac_f32_e32 v35, v6, v7
	v_cvt_pk_bf16_f32 v5, v5, v35
	ds_write_b16 v4, v5 offset:44064
	ds_write_b16_d16_hi v4, v5 offset:44336
	global_load_dwordx2 v[6:7], v66, s[14:15] offset:656
	global_load_dwordx2 v[34:35], v66, s[16:17] offset:656
	v_mul_f32_e32 v5, v28, v48
	s_waitcnt vmcnt(0)
	v_fma_f32 v5, v5, v6, v34
	v_mul_f32_e32 v6, v26, v48
	v_fmac_f32_e32 v35, v6, v7
	v_cvt_pk_bf16_f32 v5, v5, v35
	ds_write_b16 v4, v5 offset:44608
	ds_write_b16_d16_hi v4, v5 offset:44880
	global_load_dwordx2 v[6:7], v66, s[14:15] offset:664
	global_load_dwordx2 v[34:35], v66, s[16:17] offset:664
	v_mul_f32_e32 v5, v24, v48
	s_waitcnt vmcnt(0)
	v_fma_f32 v5, v5, v6, v34
	v_mul_f32_e32 v6, v20, v48
	v_fmac_f32_e32 v35, v6, v7
	v_cvt_pk_bf16_f32 v5, v5, v35
	ds_write_b16 v4, v5 offset:45152
	ds_write_b16_d16_hi v4, v5 offset:45424
	global_load_dwordx2 v[6:7], v66, s[14:15] offset:768
	global_load_dwordx2 v[34:35], v66, s[16:17] offset:768
	v_mul_f32_e32 v5, v23, v48
	s_waitcnt vmcnt(0)
	v_fma_f32 v5, v5, v6, v34
	v_mul_f32_e32 v6, v18, v48
	v_fmac_f32_e32 v35, v6, v7
	v_cvt_pk_bf16_f32 v5, v5, v35
	ds_write_b16 v4, v5 offset:52224
	ds_write_b16_d16_hi v4, v5 offset:52496
	global_load_dwordx2 v[6:7], v66, s[14:15] offset:776
	global_load_dwordx2 v[34:35], v66, s[16:17] offset:776
	v_mul_f32_e32 v5, v15, v48
	s_waitcnt vmcnt(0)
	v_fma_f32 v5, v5, v6, v34
	v_mul_f32_e32 v6, v14, v48
	v_fmac_f32_e32 v35, v6, v7
	v_cvt_pk_bf16_f32 v5, v5, v35
	ds_write_b16 v4, v5 offset:52768
	ds_write_b16_d16_hi v4, v5 offset:53040
	global_load_dwordx2 v[6:7], v66, s[14:15] offset:784
	global_load_dwordx2 v[14:15], v66, s[16:17] offset:784
	v_mul_f32_e32 v5, v13, v48
	s_waitcnt vmcnt(0)
	v_fma_f32 v5, v5, v6, v14
	v_mul_f32_e32 v6, v12, v48
	v_fmac_f32_e32 v15, v6, v7
	v_cvt_pk_bf16_f32 v5, v5, v15
	ds_write_b16 v4, v5 offset:53312
	ds_write_b16_d16_hi v4, v5 offset:53584
	global_load_dwordx2 v[6:7], v66, s[14:15] offset:792
	global_load_dwordx2 v[12:13], v66, s[16:17] offset:792
	v_mul_f32_e32 v5, v11, v48
	v_or_b32_e32 v14, s3, v8
	s_waitcnt vmcnt(0)
	v_fma_f32 v5, v5, v6, v12
	v_fmac_f32_e32 v13, v0, v7
	v_cvt_pk_bf16_f32 v0, v5, v13
	ds_write_b16 v4, v0 offset:53856
	ds_write_b16_d16_hi v4, v0 offset:54128
	global_load_dwordx2 v[6:7], v66, s[14:15] offset:896
	global_load_dwordx2 v[12:13], v66, s[16:17] offset:896
	v_mul_f32_e32 v0, v33, v48
	v_mul_f32_e32 v5, v31, v48
	s_waitcnt vmcnt(0)
	v_fma_f32 v0, v0, v6, v12
	v_fmac_f32_e32 v13, v5, v7
	v_cvt_pk_bf16_f32 v0, v0, v13
	ds_write_b16 v4, v0 offset:60928
	ds_write_b16_d16_hi v4, v0 offset:61200
	global_load_dwordx2 v[6:7], v66, s[14:15] offset:904
	global_load_dwordx2 v[12:13], v66, s[16:17] offset:904
	v_mul_f32_e32 v0, v29, v48
	v_mul_f32_e32 v5, v27, v48
	s_waitcnt vmcnt(0)
	v_fma_f32 v0, v0, v6, v12
	v_fmac_f32_e32 v13, v5, v7
	v_cvt_pk_bf16_f32 v0, v0, v13
	ds_write_b16 v4, v0 offset:61472
	ds_write_b16_d16_hi v4, v0 offset:61744
	global_load_dwordx2 v[6:7], v66, s[14:15] offset:912
	global_load_dwordx2 v[12:13], v66, s[16:17] offset:912
	v_mul_f32_e32 v0, v25, v48
	v_mul_f32_e32 v5, v22, v48
	s_waitcnt vmcnt(0)
	v_fma_f32 v0, v0, v6, v12
	v_fmac_f32_e32 v13, v5, v7
	v_cvt_pk_bf16_f32 v0, v0, v13
	ds_write_b16 v4, v0 offset:62016
	ds_write_b16_d16_hi v4, v0 offset:62288
	global_load_dwordx2 v[6:7], v66, s[14:15] offset:920
	global_load_dwordx2 v[12:13], v66, s[16:17] offset:920
	v_mul_f32_e32 v0, v19, v48
	v_mul_f32_e32 v5, v17, v48
	s_waitcnt vmcnt(0)
	v_fma_f32 v0, v0, v6, v12
	v_fmac_f32_e32 v13, v5, v7
	v_cvt_pk_bf16_f32 v0, v0, v13
	ds_write_b16 v4, v0 offset:62560
	ds_write_b16_d16_hi v4, v0 offset:62832
	v_or_b32_e32 v0, s5, v8
	v_mul_lo_u32 v0, v0, s7
	s_ashr_i32 s7, s6, 31
	s_lshl_b64 s[20:21], s[6:7], 15
	v_lshlrev_b32_e32 v4, 3, v10
	s_add_u32 s12, s12, s24
	v_add_lshl_u32 v11, v0, v4, 1
	s_addc_u32 s13, s13, s25
	v_or_b32_e32 v4, s2, v8
	v_readlane_b32 s2, v255, 10
	v_readlane_b32 s3, v255, 11
	s_add_u32 s2, s10, s2
	v_lshlrev_b32_e32 v6, 8, v8
	v_lshlrev_b32_e32 v7, 4, v10
	s_addc_u32 s3, s11, s3
	v_or3_b32 v6, s20, v6, v7
	v_mov_b32_e32 v7, s21
	v_lshl_add_u64 v[52:53], s[2:3], 0, v[6:7]
	v_lshl_or_b32 v6, v10, 2, s5
	v_mov_b32_e32 v5, s22
	v_ashrrev_i32_e32 v7, 31, v6
	v_lshlrev_b64 v[54:55], 1, v[6:7]
	v_lshlrev_b64 v[6:7], 11, v[4:5]
	v_mad_u64_u32 v[58:59], s[2:3], v4, s85, v[2:3]
	v_mov_b32_e32 v2, 0x1080
	v_xor_b32_e32 v0, 0x80, v21
	v_cmp_gt_u32_e64 s[6:7], 32, v9
	v_lshl_add_u64 v[50:51], v[4:5], 3, s[12:13]
	v_lshl_add_u64 v[56:57], s[8:9], 0, v[6:7]
	v_mad_i32_i24 v59, s22, v2, v59
	s_mov_b32 s5, 0
	s_mov_b64 s[20:21], 0
	v_add_u32_e32 v17, 0, v11
	s_waitcnt lgkmcnt(0)
	s_barrier
	s_branch .LBB0_837
